# conversion loads nt (touch-once f32 weights); conversion job index decomposed so a workgroup writes adjacent k-chunks (full lines)
# speedup vs baseline: 1.0046x; 1.0046x over previous
.LBB0_744:
	s_andn2_b64 vcc, exec, s[14:15]
	s_mov_b64 s[72:73], 0
	s_cbranch_vccnz .LBB0_747
	s_load_dwordx2 s[12:13], s[6:7], 0xb0
	s_load_dwordx2 s[14:15], s[6:7], 0x38
	s_add_i32 s37, s35, 0xffff9000
	s_mov_b64 s[70:71], 0x2000
	s_mov_b64 s[62:63], 0x800
	s_waitcnt lgkmcnt(0)
	s_add_u32 s12, s12, 0x4000000
	s_addc_u32 s13, s13, 0
	s_add_u32 s68, s14, 0x2000
	s_addc_u32 s69, s15, 0
	s_movk_i32 s38, 0x40
	s_mov_b64 s[64:65], s[18:19]
	s_branch .LBB0_748

.LBB0_747:
	s_mov_b64 s[70:71], 0x800
	s_mov_b64 s[62:63], 0x2000
	s_movk_i32 s38, 0x100
	s_mov_b64 s[64:65], s[16:17]
	s_mov_b64 s[68:69], 0
.LBB0_748:
	s_mov_b64 s[14:15], 0
	s_mov_b64 s[74:75], 0
	s_andn2_b64 vcc, exec, s[72:73]
	s_mov_b64 s[72:73], 0
	s_cbranch_vccnz .LBB0_750
	s_load_dwordx4 s[12:15], s[6:7], 0xa0
	s_add_i32 s37, s35, 0xffffa000
	s_mov_b64 s[68:69], 0
	s_mov_b64 s[62:63], 0x800
	s_movk_i32 s38, 0x40
	s_mov_b64 s[72:73], -1
	s_mov_b64 s[64:65], s[20:21]
	s_mov_b64 s[70:71], 0x800
.LBB0_750:
	s_andn2_b64 vcc, exec, s[74:75]
	s_cbranch_vccnz .LBB0_752
	s_waitcnt lgkmcnt(0)
	s_load_dwordx2 s[12:13], s[6:7], 0xb8
	s_add_i32 s37, s35, 0xffffc000
	s_mov_b64 s[70:71], 0x800
	s_mov_b64 s[62:63], 0x2000
	s_mov_b64 s[14:15], 0
	s_movk_i32 s38, 0x100
	s_mov_b64 s[72:73], 0
	s_mov_b64 s[64:65], s[22:23]
	s_mov_b64 s[68:69], 0

.LBB0_753:
	s_andn2_b64 vcc, exec, s[74:75]
	s_cbranch_vccnz .LBB0_755
	s_waitcnt lgkmcnt(0)
	s_load_dwordx2 s[12:13], s[6:7], 0xb0
	s_load_dwordx2 s[68:69], s[6:7], 0x38
	s_add_i32 s37, s35, 0xffffe000
	s_mov_b64 s[70:71], 0x2000
	s_mov_b64 s[62:63], 0x800
	s_mov_b64 s[14:15], 0
	s_movk_i32 s38, 0x40
	s_mov_b64 s[72:73], 0
	s_mov_b64 s[64:65], s[24:25]

.LBB0_756:
	s_andn2_b64 vcc, exec, s[74:75]
	s_cbranch_vccnz .LBB0_758
	s_waitcnt lgkmcnt(0)
	s_load_dwordx2 s[12:13], s[6:7], 0x58
	s_add_i32 s37, s35, 0xffffe800
	s_mov_b64 s[62:63], 0x800
	s_mov_b64 s[14:15], 0
	s_movk_i32 s38, 0x40
	s_mov_b64 s[72:73], 0
	s_mov_b64 s[64:65], s[26:27]
	s_mov_b64 s[70:71], 0x800
	s_mov_b64 s[68:69], 0

.LBB0_759:
	s_waitcnt lgkmcnt(0)
	s_load_dwordx2 s[68:69], s[6:7], 0x30
	s_load_dwordx2 s[12:13], s[6:7], 0x48
	s_mov_b64 s[72:73], 0
	s_movk_i32 s38, 0x40
	s_mov_b64 s[14:15], 0
	s_mov_b64 s[62:63], 0x800
	s_mov_b64 s[70:71], 0x1800
	s_mov_b32 s37, s35
.LBB0_760:
	v_cvt_f32_u32_e32 v1, s38
	s_sub_i32 s42, 0, s38
	s_abs_i32 s39, s37
	s_ashr_i32 s31, s37, 31
	v_rcp_iflag_f32_e32 v1, v1
	s_nop 0
	v_mul_f32_e32 v1, 0x4f7ffffe, v1
	v_cvt_u32_f32_e32 v1, v1
	s_nop 0
	v_readfirstlane_b32 s43, v1
	s_mul_i32 s42, s42, s43
	s_mul_hi_u32 s42, s43, s42
	s_add_i32 s43, s43, s42
	s_mul_hi_u32 s42, s39, s43
	s_mul_i32 s43, s42, s38
	s_sub_i32 s39, s39, s43
	s_add_i32 s44, s42, 1
	s_sub_i32 s43, s39, s38
	s_cmp_ge_u32 s39, s38
	s_cselect_b32 s42, s44, s42
	s_cselect_b32 s39, s43, s39
	s_add_i32 s43, s42, 1
	s_cmp_ge_u32 s39, s38
	s_cselect_b32 s39, s43, s42
	s_xor_b32 s39, s39, s31
	s_sub_i32 s39, s39, s31
	s_mul_i32 s31, s39, s38
	s_sub_i32 s38, s37, s31
	s_mov_b32 s31, s38
	s_mov_b32 s38, s39
	s_mov_b32 s39, s31
	s_lshl_b32 s37, s38, 6
	s_andn2_b64 vcc, exec, s[66:67]
	s_mov_b32 s42, s37
	s_cbranch_vccnz .LBB0_765
	s_cmp_gt_i32 s38, 63
	s_mov_b64 s[66:67], -1
	s_cbranch_scc0 .LBB0_763
	s_add_i32 s42, s37, 0xfffff000
	s_mov_b64 s[66:67], 0

.LBB0_765:
	s_lshl_b32 s66, s39, 5
	s_lshl_b32 s39, s38, 5
	s_and_b32 s31, s37, 64
	s_and_b32 s39, s39, 0xffffff80
	s_or_b32 s31, s39, s31
	s_bitcmp0_b32 s38, 1
	s_waitcnt lgkmcnt(0)
	s_cselect_b32 s38, s12, s14
	s_cselect_b32 s39, s13, s15
	s_and_b64 s[14:15], s[72:73], exec
	s_cselect_b32 s15, s38, s12
	s_cselect_b32 s12, s31, s42
	s_cselect_b32 s14, s39, s13
	s_ashr_i32 s13, s12, 31
	s_lshl_b64 s[12:13], s[12:13], 2
	s_add_u32 s15, s15, s12
	s_addc_u32 s14, s14, s13
	s_ashr_i32 s67, s66, 31
	s_mul_i32 s12, s70, s67
	s_mul_hi_u32 s13, s70, s66
	s_add_i32 s12, s13, s12
	s_mul_i32 s13, s71, s66
	s_add_i32 s13, s12, s13
	s_mul_i32 s12, s70, s66
	s_lshl_b64 s[12:13], s[12:13], 2
	s_add_u32 s12, s15, s12
	s_addc_u32 s13, s14, s13
	v_lshl_add_u64 v[4:5], s[12:13], 0, v[192:193]
	global_load_dword v2, v192, s[12:13] nt
	s_lshl_b64 s[12:13], s[70:71], 2
	v_lshl_add_u64 v[4:5], v[4:5], 0, s[12:13]
	v_lshl_add_u64 v[6:7], v[4:5], 0, s[12:13]
	v_lshl_add_u64 v[8:9], v[6:7], 0, s[12:13]
	v_lshl_add_u64 v[10:11], v[8:9], 0, s[12:13]
	v_lshl_add_u64 v[12:13], v[10:11], 0, s[12:13]
	v_lshl_add_u64 v[14:15], v[12:13], 0, s[12:13]
	v_lshl_add_u64 v[16:17], v[14:15], 0, s[12:13]
	global_load_dword v3, v[4:5], off nt
	s_nop 0
	global_load_dword v6, v[6:7], off nt
	s_nop 0
	global_load_dword v7, v[8:9], off nt
	s_nop 0
	global_load_dword v8, v[10:11], off nt
	global_load_dword v9, v[12:13], off nt
	s_nop 0
	global_load_dword v12, v[14:15], off nt
	global_load_dword v13, v[16:17], off nt
	v_lshl_add_u64 v[10:11], v[16:17], 0, s[12:13]
	global_load_dword v4, v[10:11], off nt
	v_lshl_add_u64 v[10:11], v[10:11], 0, s[12:13]
	v_lshl_add_u64 v[14:15], v[10:11], 0, s[12:13]
	global_load_dword v5, v[10:11], off nt
	s_cmp_eq_u64 s[68:69], 0
	global_load_dword v10, v[14:15], off nt
	v_lshl_add_u64 v[14:15], v[14:15], 0, s[12:13]
	v_lshl_add_u64 v[16:17], v[14:15], 0, s[12:13]
	global_load_dword v11, v[14:15], off nt
	s_nop 0
	global_load_dword v14, v[16:17], off nt
	v_lshl_add_u64 v[16:17], v[16:17], 0, s[12:13]
	global_load_dword v15, v[16:17], off nt
	v_lshl_add_u64 v[16:17], v[16:17], 0, s[12:13]
	global_load_dword v18, v[16:17], off nt
	v_lshl_add_u64 v[16:17], v[16:17], 0, s[12:13]
	v_lshl_add_u64 v[20:21], v[16:17], 0, s[12:13]
	global_load_dword v19, v[16:17], off nt
	s_nop 0
	global_load_dword v16, v[20:21], off nt
	v_lshl_add_u64 v[20:21], v[20:21], 0, s[12:13]
	v_lshl_add_u64 v[22:23], v[20:21], 0, s[12:13]
	global_load_dword v17, v[20:21], off nt
	s_nop 0
	global_load_dword v20, v[22:23], off nt
	v_lshl_add_u64 v[22:23], v[22:23], 0, s[12:13]
	v_lshl_add_u64 v[24:25], v[22:23], 0, s[12:13]
	global_load_dword v21, v[22:23], off nt
	s_nop 0
	global_load_dword v22, v[24:25], off nt
	v_lshl_add_u64 v[24:25], v[24:25], 0, s[12:13]
	global_load_dword v23, v[24:25], off nt
	v_lshl_add_u64 v[24:25], v[24:25], 0, s[12:13]
	global_load_dword v26, v[24:25], off nt
	v_lshl_add_u64 v[24:25], v[24:25], 0, s[12:13]
	v_lshl_add_u64 v[28:29], v[24:25], 0, s[12:13]
	global_load_dword v27, v[24:25], off nt
	s_nop 0
	global_load_dword v24, v[28:29], off nt
	v_lshl_add_u64 v[28:29], v[28:29], 0, s[12:13]
	v_lshl_add_u64 v[30:31], v[28:29], 0, s[12:13]
	global_load_dword v25, v[28:29], off nt
	s_nop 0
	global_load_dword v28, v[30:31], off nt
	v_lshl_add_u64 v[30:31], v[30:31], 0, s[12:13]
	v_lshl_add_u64 v[32:33], v[30:31], 0, s[12:13]
	global_load_dword v29, v[30:31], off nt
	s_nop 0
	global_load_dword v30, v[32:33], off nt
	v_lshl_add_u64 v[32:33], v[32:33], 0, s[12:13]
	v_lshl_add_u64 v[34:35], v[32:33], 0, s[12:13]
	global_load_dword v31, v[32:33], off nt
	s_nop 0
	global_load_dword v32, v[34:35], off nt
	v_lshl_add_u64 v[34:35], v[34:35], 0, s[12:13]
	global_load_dword v33, v[34:35], off nt
	s_cbranch_scc1 .LBB0_736
	s_lshl_b64 s[12:13], s[66:67], 2
	s_add_u32 s12, s68, s12
	s_addc_u32 s13, s69, s13
	global_load_dwordx4 v[34:37], v193, s[12:13]
	global_load_dwordx4 v[38:41], v193, s[12:13] offset:16
	global_load_dwordx4 v[42:45], v193, s[12:13] offset:32
	global_load_dwordx4 v[46:49], v193, s[12:13] offset:48
	global_load_dwordx4 v[50:53], v193, s[12:13] offset:64
	global_load_dwordx4 v[54:57], v193, s[12:13] offset:80
	global_load_dwordx4 v[58:61], v193, s[12:13] offset:96
	global_load_dwordx4 v[62:65], v193, s[12:13] offset:112
	s_waitcnt vmcnt(7)
	v_pk_mul_f32 v[2:3], v[2:3], v[34:35]
	v_pk_mul_f32 v[6:7], v[6:7], v[36:37]
	s_waitcnt vmcnt(6)
	v_pk_mul_f32 v[8:9], v[8:9], v[38:39]
	v_pk_mul_f32 v[12:13], v[12:13], v[40:41]
	s_waitcnt vmcnt(5)
	v_pk_mul_f32 v[4:5], v[4:5], v[42:43]
	v_pk_mul_f32 v[10:11], v[10:11], v[44:45]
	s_waitcnt vmcnt(4)
	v_pk_mul_f32 v[14:15], v[14:15], v[46:47]
	v_pk_mul_f32 v[18:19], v[18:19], v[48:49]
	s_waitcnt vmcnt(3)
	v_pk_mul_f32 v[16:17], v[16:17], v[50:51]
	v_pk_mul_f32 v[20:21], v[20:21], v[52:53]
	s_waitcnt vmcnt(2)
	v_pk_mul_f32 v[22:23], v[22:23], v[54:55]
	v_pk_mul_f32 v[26:27], v[26:27], v[56:57]
	s_waitcnt vmcnt(1)
	v_pk_mul_f32 v[24:25], v[24:25], v[58:59]
	v_pk_mul_f32 v[28:29], v[28:29], v[60:61]
	s_waitcnt vmcnt(0)
	v_pk_mul_f32 v[30:31], v[30:31], v[62:63]
	v_pk_mul_f32 v[32:33], v[32:33], v[64:65]
	s_branch .LBB0_736

.LBB0_801:
	s_lshl_b32 s66, s38, 5
	s_lshl_b32 s38, s37, 5
	s_and_b32 s31, s36, 64
	s_and_b32 s38, s38, 0xffffff80
	s_or_b32 s31, s38, s31
	s_bitcmp0_b32 s37, 1
	s_waitcnt lgkmcnt(0)
	s_cselect_b32 s37, s12, s14
	s_cselect_b32 s38, s13, s15
	s_and_b64 s[14:15], s[72:73], exec
	s_cselect_b32 s15, s37, s12
	s_cselect_b32 s12, s31, s39
	s_cselect_b32 s14, s38, s13
	s_ashr_i32 s13, s12, 31
	s_lshl_b64 s[12:13], s[12:13], 2
	s_add_u32 s15, s15, s12
	s_addc_u32 s14, s14, s13
	s_ashr_i32 s67, s66, 31
	s_mul_i32 s12, s70, s67
	s_mul_hi_u32 s13, s70, s66
	s_add_i32 s12, s13, s12
	s_mul_i32 s13, s71, s66
	s_add_i32 s13, s12, s13
	s_mul_i32 s12, s70, s66
	s_lshl_b64 s[12:13], s[12:13], 2
	s_add_u32 s12, s15, s12
	s_addc_u32 s13, s14, s13
	v_lshl_add_u64 v[4:5], s[12:13], 0, v[192:193]
	global_load_dword v2, v192, s[12:13] nt
	s_lshl_b64 s[12:13], s[70:71], 2
	v_lshl_add_u64 v[4:5], v[4:5], 0, s[12:13]
	v_lshl_add_u64 v[6:7], v[4:5], 0, s[12:13]
	v_lshl_add_u64 v[8:9], v[6:7], 0, s[12:13]
	v_lshl_add_u64 v[10:11], v[8:9], 0, s[12:13]
	v_lshl_add_u64 v[12:13], v[10:11], 0, s[12:13]
	v_lshl_add_u64 v[14:15], v[12:13], 0, s[12:13]
	v_lshl_add_u64 v[16:17], v[14:15], 0, s[12:13]
	global_load_dword v3, v[4:5], off nt
	s_nop 0
	global_load_dword v6, v[6:7], off nt
	s_nop 0
	global_load_dword v7, v[8:9], off nt
	s_nop 0
	global_load_dword v8, v[10:11], off nt
	global_load_dword v9, v[12:13], off nt
	s_nop 0
	global_load_dword v12, v[14:15], off nt
	global_load_dword v13, v[16:17], off nt
	v_lshl_add_u64 v[10:11], v[16:17], 0, s[12:13]
	global_load_dword v4, v[10:11], off nt
	v_lshl_add_u64 v[10:11], v[10:11], 0, s[12:13]
	v_lshl_add_u64 v[14:15], v[10:11], 0, s[12:13]
	global_load_dword v5, v[10:11], off nt
	s_cmp_eq_u64 s[68:69], 0
	global_load_dword v10, v[14:15], off nt
	v_lshl_add_u64 v[14:15], v[14:15], 0, s[12:13]
	v_lshl_add_u64 v[16:17], v[14:15], 0, s[12:13]
	global_load_dword v11, v[14:15], off nt
	s_nop 0
	global_load_dword v14, v[16:17], off nt
	v_lshl_add_u64 v[16:17], v[16:17], 0, s[12:13]
	global_load_dword v15, v[16:17], off nt
	v_lshl_add_u64 v[16:17], v[16:17], 0, s[12:13]
	global_load_dword v18, v[16:17], off nt
	v_lshl_add_u64 v[16:17], v[16:17], 0, s[12:13]
	v_lshl_add_u64 v[20:21], v[16:17], 0, s[12:13]
	global_load_dword v19, v[16:17], off nt
	s_nop 0
	global_load_dword v16, v[20:21], off nt
	v_lshl_add_u64 v[20:21], v[20:21], 0, s[12:13]
	v_lshl_add_u64 v[22:23], v[20:21], 0, s[12:13]
	global_load_dword v17, v[20:21], off nt
	s_nop 0
	global_load_dword v20, v[22:23], off nt
	v_lshl_add_u64 v[22:23], v[22:23], 0, s[12:13]
	v_lshl_add_u64 v[24:25], v[22:23], 0, s[12:13]
	global_load_dword v21, v[22:23], off nt
	s_nop 0
	global_load_dword v22, v[24:25], off nt
	v_lshl_add_u64 v[24:25], v[24:25], 0, s[12:13]
	global_load_dword v23, v[24:25], off nt
	v_lshl_add_u64 v[24:25], v[24:25], 0, s[12:13]
	global_load_dword v26, v[24:25], off nt
	v_lshl_add_u64 v[24:25], v[24:25], 0, s[12:13]
	v_lshl_add_u64 v[28:29], v[24:25], 0, s[12:13]
	global_load_dword v27, v[24:25], off nt
	s_nop 0
	global_load_dword v24, v[28:29], off nt
	v_lshl_add_u64 v[28:29], v[28:29], 0, s[12:13]
	v_lshl_add_u64 v[30:31], v[28:29], 0, s[12:13]
	global_load_dword v25, v[28:29], off nt
	s_nop 0
	global_load_dword v28, v[30:31], off nt
	v_lshl_add_u64 v[30:31], v[30:31], 0, s[12:13]
	v_lshl_add_u64 v[32:33], v[30:31], 0, s[12:13]
	global_load_dword v29, v[30:31], off nt
	s_nop 0
	global_load_dword v30, v[32:33], off nt
	v_lshl_add_u64 v[32:33], v[32:33], 0, s[12:13]
	v_lshl_add_u64 v[34:35], v[32:33], 0, s[12:13]
	global_load_dword v31, v[32:33], off nt
	s_nop 0
	global_load_dword v32, v[34:35], off nt
	v_lshl_add_u64 v[34:35], v[34:35], 0, s[12:13]
	global_load_dword v33, v[34:35], off nt
	s_cbranch_scc1 .LBB0_772
	s_lshl_b64 s[12:13], s[66:67], 2
	s_add_u32 s12, s68, s12
	s_addc_u32 s13, s69, s13
	global_load_dwordx4 v[34:37], v193, s[12:13]
	global_load_dwordx4 v[38:41], v193, s[12:13] offset:16
	global_load_dwordx4 v[42:45], v193, s[12:13] offset:32
	global_load_dwordx4 v[46:49], v193, s[12:13] offset:48
	global_load_dwordx4 v[50:53], v193, s[12:13] offset:64
	global_load_dwordx4 v[54:57], v193, s[12:13] offset:80
	global_load_dwordx4 v[58:61], v193, s[12:13] offset:96
	global_load_dwordx4 v[62:65], v193, s[12:13] offset:112
	s_waitcnt vmcnt(7)
	v_pk_mul_f32 v[2:3], v[2:3], v[34:35]
	v_pk_mul_f32 v[6:7], v[6:7], v[36:37]
	s_waitcnt vmcnt(6)
	v_pk_mul_f32 v[8:9], v[8:9], v[38:39]
	v_pk_mul_f32 v[12:13], v[12:13], v[40:41]
	s_waitcnt vmcnt(5)
	v_pk_mul_f32 v[4:5], v[4:5], v[42:43]
	v_pk_mul_f32 v[10:11], v[10:11], v[44:45]
	s_waitcnt vmcnt(4)
	v_pk_mul_f32 v[14:15], v[14:15], v[46:47]
	v_pk_mul_f32 v[18:19], v[18:19], v[48:49]
	s_waitcnt vmcnt(3)
	v_pk_mul_f32 v[16:17], v[16:17], v[50:51]
	v_pk_mul_f32 v[20:21], v[20:21], v[52:53]
	s_waitcnt vmcnt(2)
	v_pk_mul_f32 v[22:23], v[22:23], v[54:55]
	v_pk_mul_f32 v[26:27], v[26:27], v[56:57]
	s_waitcnt vmcnt(1)
	v_pk_mul_f32 v[24:25], v[24:25], v[58:59]
	v_pk_mul_f32 v[28:29], v[28:29], v[60:61]
	s_waitcnt vmcnt(0)
	v_pk_mul_f32 v[30:31], v[30:31], v[62:63]
	v_pk_mul_f32 v[32:33], v[32:33], v[64:65]
	s_branch .LBB0_772

.LBB0_813:
	s_ashr_i32 s19, s18, 31
	s_lshl_b32 s16, s27, 5
	s_lshl_b64 s[18:19], s[18:19], 2
	s_add_u32 s18, s12, s18
	s_addc_u32 s19, s13, s19
	s_ashr_i32 s17, s16, 31
	s_mul_i32 s27, s27, 0xc0000
	s_mul_hi_i32 s30, s16, 0x6000
	s_add_u32 s18, s18, s27
	s_addc_u32 s19, s19, s30
	v_lshl_add_u64 v[28:29], s[18:19], 0, v[192:193]
	v_add_co_u32_e32 v2, vcc, s45, v28
	s_mov_b32 s27, 0xc000
	s_nop 0
	v_addc_co_u32_e32 v3, vcc, 0, v29, vcc
	v_add_co_u32_e32 v4, vcc, s27, v28
	s_mov_b32 s27, 0x18000
	s_nop 0
	v_addc_co_u32_e32 v5, vcc, 0, v29, vcc
	v_add_co_u32_e32 v6, vcc, s4, v28
	s_nop 1
	v_addc_co_u32_e32 v7, vcc, 0, v29, vcc
	v_add_co_u32_e32 v8, vcc, s27, v28
	s_mov_b32 s27, 0x1e000
	s_nop 0
	v_addc_co_u32_e32 v9, vcc, 0, v29, vcc
	v_add_co_u32_e32 v12, vcc, s27, v28
	s_mov_b32 s27, 0x24000
	s_nop 0
	v_addc_co_u32_e32 v13, vcc, 0, v29, vcc
	v_add_co_u32_e32 v14, vcc, s27, v28
	s_mov_b32 s27, 0x2a000
	s_nop 0
	v_addc_co_u32_e32 v15, vcc, 0, v29, vcc
	v_add_co_u32_e32 v16, vcc, s27, v28
	s_mov_b32 s27, 0x30000
	s_nop 0
	v_addc_co_u32_e32 v17, vcc, 0, v29, vcc
	v_add_co_u32_e32 v18, vcc, s27, v28
	s_mov_b32 s27, 0x36000
	s_nop 0
	v_addc_co_u32_e32 v19, vcc, 0, v29, vcc
	global_load_dword v11, v[2:3], off nt
	s_nop 0
	global_load_dword v4, v[4:5], off nt
	s_nop 0
	global_load_dword v5, v[6:7], off nt
	s_nop 0
	global_load_dword v6, v[8:9], off nt
	global_load_dword v7, v[12:13], off nt
	s_nop 0
	global_load_dword v8, v[14:15], off nt
	global_load_dword v9, v[16:17], off nt
	global_load_dword v2, v[18:19], off nt
	v_add_co_u32_e32 v12, vcc, s27, v28
	s_mov_b32 s27, 0x3c000
	s_nop 0
	v_addc_co_u32_e32 v13, vcc, 0, v29, vcc
	v_add_co_u32_e32 v14, vcc, s27, v28
	s_mov_b32 s27, 0x42000
	s_nop 0
	v_addc_co_u32_e32 v15, vcc, 0, v29, vcc
	v_add_co_u32_e32 v16, vcc, s27, v28
	s_mov_b32 s27, 0x48000
	s_nop 0
	v_addc_co_u32_e32 v17, vcc, 0, v29, vcc
	v_add_co_u32_e32 v18, vcc, s27, v28
	s_mov_b32 s27, 0x4e000
	s_nop 0
	v_addc_co_u32_e32 v19, vcc, 0, v29, vcc
	v_add_co_u32_e32 v20, vcc, s27, v28
	s_mov_b32 s27, 0x54000
	s_nop 0
	v_addc_co_u32_e32 v21, vcc, 0, v29, vcc
	v_add_co_u32_e32 v22, vcc, s27, v28
	s_mov_b32 s27, 0x5a000
	s_nop 0
	v_addc_co_u32_e32 v23, vcc, 0, v29, vcc
	v_add_co_u32_e32 v24, vcc, s27, v28
	s_mov_b32 s27, 0x60000
	s_nop 0
	v_addc_co_u32_e32 v25, vcc, 0, v29, vcc
	v_add_co_u32_e32 v26, vcc, s27, v28
	s_mov_b32 s27, 0x66000
	s_nop 0
	v_addc_co_u32_e32 v27, vcc, 0, v29, vcc
	global_load_dword v3, v[12:13], off nt
	s_nop 0
	global_load_dword v14, v[14:15], off nt
	s_nop 0
	global_load_dword v15, v[16:17], off nt
	s_nop 0
	global_load_dword v16, v[18:19], off nt
	global_load_dword v17, v[20:21], off nt
	s_nop 0
	global_load_dword v18, v[22:23], off nt
	global_load_dword v19, v[24:25], off nt
	global_load_dword v12, v[26:27], off nt
	v_add_co_u32_e32 v20, vcc, s27, v28
	s_mov_b32 s27, 0x6c000
	s_nop 0
	v_addc_co_u32_e32 v21, vcc, 0, v29, vcc
	v_add_co_u32_e32 v22, vcc, s27, v28
	s_mov_b32 s27, 0x72000
	s_nop 0
	v_addc_co_u32_e32 v23, vcc, 0, v29, vcc
	v_add_co_u32_e32 v24, vcc, s27, v28
	s_mov_b32 s27, 0x78000
	s_nop 0
	v_addc_co_u32_e32 v25, vcc, 0, v29, vcc
	v_add_co_u32_e32 v26, vcc, s27, v28
	s_mov_b32 s27, 0x7e000
	s_nop 0
	v_addc_co_u32_e32 v27, vcc, 0, v29, vcc
	v_add_co_u32_e32 v30, vcc, s27, v28
	s_mov_b32 s27, 0x84000
	s_nop 0
	v_addc_co_u32_e32 v31, vcc, 0, v29, vcc
	v_add_co_u32_e32 v32, vcc, s27, v28
	s_mov_b32 s27, 0x8a000
	s_nop 0
	v_addc_co_u32_e32 v33, vcc, 0, v29, vcc
	v_add_co_u32_e32 v34, vcc, s27, v28
	s_mov_b32 s27, 0x96000
	s_nop 0
	v_addc_co_u32_e32 v35, vcc, 0, v29, vcc
	v_add_co_u32_e32 v36, vcc, s5, v28
	s_nop 1
	v_addc_co_u32_e32 v37, vcc, 0, v29, vcc
	global_load_dword v13, v[20:21], off nt
	s_nop 0
	global_load_dword v22, v[22:23], off nt
	s_nop 0
	global_load_dword v23, v[24:25], off nt
	s_nop 0
	global_load_dword v24, v[26:27], off nt
	global_load_dword v25, v[30:31], off nt
	s_nop 0
	global_load_dword v26, v[32:33], off nt
	global_load_dword v27, v[34:35], off nt
	global_load_dword v20, v[36:37], off nt
	v_add_co_u32_e32 v30, vcc, s27, v28
	s_mov_b32 s27, 0x9c000
	s_nop 0
	v_addc_co_u32_e32 v31, vcc, 0, v29, vcc
	v_add_co_u32_e32 v32, vcc, s27, v28
	s_mov_b32 s27, 0xa2000
	s_nop 0
	v_addc_co_u32_e32 v33, vcc, 0, v29, vcc
	v_add_co_u32_e32 v34, vcc, s27, v28
	s_mov_b32 s27, 0xa8000
	s_nop 0
	v_addc_co_u32_e32 v35, vcc, 0, v29, vcc
	v_add_co_u32_e32 v36, vcc, s27, v28
	s_nop 1
	v_addc_co_u32_e32 v37, vcc, 0, v29, vcc
	v_add_co_u32_e32 v40, vcc, 0xae000, v28
	s_nop 1
	v_addc_co_u32_e32 v41, vcc, 0, v29, vcc
	v_add_co_u32_e32 v42, vcc, 0xb4000, v28
	s_nop 1
	v_addc_co_u32_e32 v43, vcc, 0, v29, vcc
	v_add_co_u32_e32 v44, vcc, 0xba000, v28
	s_nop 1
	v_addc_co_u32_e32 v45, vcc, 0, v29, vcc
	global_load_dword v10, v192, s[18:19] nt
	global_load_dword v21, v[30:31], off nt
	global_load_dword v28, v[32:33], off nt
	global_load_dword v29, v[34:35], off nt
	s_nop 0
	global_load_dword v32, v[36:37], off nt
	global_load_dword v33, v[40:41], off nt
	global_load_dword v30, v[42:43], off nt
	global_load_dword v31, v[44:45], off nt
	s_andn2_b64 vcc, exec, s[14:15]
	s_cbranch_vccnz .LBB0_808
	s_lshl_b64 s[18:19], s[16:17], 2
	s_add_u32 s18, s6, s18
	s_addc_u32 s19, s7, s19
	global_load_dwordx4 v[34:37], v193, s[18:19]
	global_load_dwordx4 v[40:43], v193, s[18:19] offset:16
	global_load_dwordx4 v[44:47], v193, s[18:19] offset:32
	global_load_dwordx4 v[48:51], v193, s[18:19] offset:48
	global_load_dwordx4 v[52:55], v193, s[18:19] offset:64
	global_load_dwordx4 v[56:59], v193, s[18:19] offset:80
	global_load_dwordx4 v[60:63], v193, s[18:19] offset:96
	global_load_dwordx4 v[64:67], v193, s[18:19] offset:112
	s_waitcnt vmcnt(7)
	v_pk_mul_f32 v[10:11], v[10:11], v[34:35]
	v_pk_mul_f32 v[4:5], v[4:5], v[36:37]
	s_waitcnt vmcnt(6)
	v_pk_mul_f32 v[6:7], v[6:7], v[40:41]
	v_pk_mul_f32 v[8:9], v[8:9], v[42:43]
	s_waitcnt vmcnt(5)
	v_pk_mul_f32 v[2:3], v[2:3], v[44:45]
	v_pk_mul_f32 v[14:15], v[14:15], v[46:47]
	s_waitcnt vmcnt(4)
	v_pk_mul_f32 v[16:17], v[16:17], v[48:49]
	v_pk_mul_f32 v[18:19], v[18:19], v[50:51]
	s_waitcnt vmcnt(3)
	v_pk_mul_f32 v[12:13], v[12:13], v[52:53]
	v_pk_mul_f32 v[22:23], v[22:23], v[54:55]
	s_waitcnt vmcnt(2)
	v_pk_mul_f32 v[24:25], v[24:25], v[56:57]
	v_pk_mul_f32 v[26:27], v[26:27], v[58:59]
	s_waitcnt vmcnt(1)
	v_pk_mul_f32 v[20:21], v[20:21], v[60:61]
	v_pk_mul_f32 v[28:29], v[28:29], v[62:63]
	s_waitcnt vmcnt(0)
	v_pk_mul_f32 v[32:33], v[32:33], v[64:65]
	v_pk_mul_f32 v[30:31], v[30:31], v[66:67]
	s_branch .LBB0_808
